# scalar overhead trimmed between PV and QK; B raises priority and drains LDS before the barrier
# speedup vs baseline: 1.0174x; 1.0174x over previous
; DI void diff_core(unsigned char* smem, const u16* qptr, const u16* kbase, const u16* vtbase, int vld,
;                   int ntb, int ntw, int nvalid, int ks0, const float* lut, int qpos, bool active, bool grpB,
;                   f32x16 (&O)[4], float& l_out) {
;     ...
;   auto qk = [&](int slot) {
;     if (grpB) __builtin_amdgcn_s_setprio(2); else __builtin_amdgcn_s_setprio(1);
;     const float ini = -m;
; #pragma unroll
;     for (int kb = 0; kb < 2; ++kb)
; #pragma unroll
;       for (int e = 0; e < 16; ++e) S[kb][e] = ini;
;     const LAS unsigned char* b = lds + slot * D_SLOT;
;     bf16x8 kf[4][2];
; #pragma unroll
;     ...
;   auto pv = [&](int slot) {
;     if (grpB) __builtin_amdgcn_s_setprio(2); else __builtin_amdgcn_s_setprio(1);
;     const LAS unsigned char* b = lds + slot * D_SLOT;
;     bf16x8 va[4], vb[4];
; #pragma unroll
;     for (int tt = 0; tt < 4; ++tt) va[tt] = *reinterpret_cast<const LAS bf16x8*>(b + voff[0] + tt * 32 * 128);
; #pragma unroll
;     for (int tt = 0; tt < 4; ++tt) vb[tt] = *reinterpret_cast<const LAS bf16x8*>(b + voff[1] + tt * 32 * 128);
;     {
;       const bf16x8 pf = __builtin_bit_cast(bf16x8, P[0]);
; #pragma unroll
;       for (int tt = 0; tt < 4; ++tt) O[tt] = MFMA(va[tt], pf, O[tt]);
;     }
; #pragma unroll
;     for (int tt = 0; tt < 4; ++tt) va[tt] = *reinterpret_cast<const LAS bf16x8*>(b + voff[2] + tt * 32 * 128);
;     {
;       const bf16x8 pf = __builtin_bit_cast(bf16x8, P[1]);
; #pragma unroll
;       for (int tt = 0; tt < 4; ++tt) O[tt] = MFMA(vb[tt], pf, O[tt]);
;     }
; #pragma unroll
;     for (int tt = 0; tt < 4; ++tt) vb[tt] = *reinterpret_cast<const LAS bf16x8*>(b + voff[3] + tt * 32 * 128);
;     {
;       const bf16x8 pf = __builtin_bit_cast(bf16x8, P[2]);
; #pragma unroll
;       for (int tt = 0; tt < 4; ++tt) O[tt] = MFMA(va[tt], pf, O[tt]);
;     }
;     {
;       const bf16x8 pf = __builtin_bit_cast(bf16x8, P[3]);
; #pragma unroll
;       for (int tt = 0; tt < 4; ++tt) O[tt] = MFMA(vb[tt], pf, O[tt]);
;     }
;     __builtin_amdgcn_sched_group_barrier(0x100, 8, 0);
;     __builtin_amdgcn_sched_group_barrier(0x008, 4, 0);
;     __builtin_amdgcn_sched_group_barrier(0x100, 4, 0);
;     __builtin_amdgcn_sched_group_barrier(0x008, 4, 0);
;     __builtin_amdgcn_sched_group_barrier(0x100, 4, 0);
;     __builtin_amdgcn_sched_group_barrier(0x008, 8, 0);
;     __builtin_amdgcn_s_setprio(0);
;   };
.LBB0_360:
	s_add_i32 s66, s64, 0x101
	s_cmp_lt_u32 s66, s16
	s_cselect_b64 s[0:1], -1, 0
	s_cmp_gt_u32 s66, s16
	s_cbranch_scc1 .LBB0_362
	s_setprio 2
	s_and_b32 s101, s65, 0x18000
	v_add_u32_e32 v248, s101, v197
	ds_read_b128 v[64:67], v248 offset:16384
	ds_read_b128 v[68:71], v248 offset:20480
	ds_read_b128 v[72:75], v248 offset:24576
	ds_read_b128 v[76:79], v248 offset:28672
	s_add_i32 s67, s65, 0xfffe8000
	s_and_b32 s67, s67, 0x18000
	v_cvt_pk_bf16_f32 v144, v96, v97
	v_cvt_pk_bf16_f32 v145, v98, v99
	v_cvt_pk_bf16_f32 v146, v100, v101
	v_cvt_pk_bf16_f32 v147, v102, v103
	v_add_f32_e32 v250, v97, v96
	v_add_f32_e32 v250, v98, v250
	s_waitcnt lgkmcnt(4)
	v_mfma_f32_32x32x16_bf16 v[48:63], v[200:203], v[144:147], v[48:63]
	v_cvt_pk_bf16_f32 v148, v104, v105
	v_add_f32_e32 v250, v99, v250
	v_add_f32_e32 v250, v100, v250
	v_add_u32_e32 v249, s101, v198
	ds_read_b128 v[80:83], v249 offset:16384
	ds_read_b128 v[84:87], v249 offset:20480
	ds_read_b128 v[88:91], v249 offset:24576
	ds_read_b128 v[92:95], v249 offset:28672
	v_mfma_f32_32x32x16_bf16 v[32:47], v[204:207], v[144:147], v[32:47]
	v_cvt_pk_bf16_f32 v149, v106, v107
	v_add_f32_e32 v250, v101, v250
	v_add_f32_e32 v250, v102, v250
	v_mfma_f32_32x32x16_bf16 v[16:31], v[208:211], v[144:147], v[16:31]
	v_cvt_pk_bf16_f32 v150, v108, v109
	v_add_f32_e32 v250, v103, v250
	v_add_f32_e32 v250, v104, v250
	v_mfma_f32_32x32x16_bf16 v[0:15], v[212:215], v[144:147], v[0:15]
	v_cvt_pk_bf16_f32 v151, v110, v111
	v_add_f32_e32 v250, v105, v250
	v_add_f32_e32 v250, v106, v250
	v_mfma_f32_32x32x16_bf16 v[48:63], v[216:219], v[148:151], v[48:63]
	v_cvt_pk_bf16_f32 v152, v112, v113
	v_add_f32_e32 v250, v107, v250
	v_add_f32_e32 v250, v108, v250
	v_mfma_f32_32x32x16_bf16 v[32:47], v[220:223], v[148:151], v[32:47]
	v_cvt_pk_bf16_f32 v153, v114, v115
	v_add_f32_e32 v250, v109, v250
	v_add_f32_e32 v250, v110, v250
	v_mfma_f32_32x32x16_bf16 v[16:31], v[224:227], v[148:151], v[16:31]
	v_cvt_pk_bf16_f32 v154, v116, v117
	v_add_f32_e32 v250, v111, v250
	v_add_f32_e32 v250, v112, v250
	v_mfma_f32_32x32x16_bf16 v[0:15], v[228:231], v[148:151], v[0:15]
	v_cvt_pk_bf16_f32 v155, v118, v119
	v_add_f32_e32 v250, v113, v250
	v_add_f32_e32 v250, v114, v250
	v_add_u32_e32 v248, s67, v177
	ds_read_b128 v[200:203], v248
	ds_read_b128 v[204:207], v248 offset:8192
	v_add_u32_e32 v249, s67, v178
	ds_read_b128 v[208:211], v249
	ds_read_b128 v[212:215], v249 offset:8192
	s_waitcnt lgkmcnt(8)
	v_mfma_f32_32x32x16_bf16 v[48:63], v[64:67], v[152:155], v[48:63]
	v_cvt_pk_bf16_f32 v156, v120, v121
	v_add_f32_e32 v250, v115, v250
	v_add_f32_e32 v250, v116, v250
	v_mfma_f32_32x32x16_bf16 v[32:47], v[68:71], v[152:155], v[32:47]
	v_cvt_pk_bf16_f32 v157, v122, v123
	v_add_f32_e32 v250, v117, v250
	v_add_f32_e32 v250, v118, v250
	v_mfma_f32_32x32x16_bf16 v[16:31], v[72:75], v[152:155], v[16:31]
	v_cvt_pk_bf16_f32 v158, v124, v125
	v_add_f32_e32 v250, v119, v250
	v_add_f32_e32 v250, v120, v250
	v_mfma_f32_32x32x16_bf16 v[0:15], v[76:79], v[152:155], v[0:15]
	v_cvt_pk_bf16_f32 v159, v126, v127
	v_add_f32_e32 v250, v121, v250
	v_add_f32_e32 v250, v122, v250
	v_add_u32_e32 v248, s67, v179
	ds_read_b128 v[216:219], v248
	ds_read_b128 v[220:223], v248 offset:8192
	v_add_u32_e32 v249, s67, v180
	ds_read_b128 v[224:227], v249
	ds_read_b128 v[228:231], v249 offset:8192
	s_waitcnt lgkmcnt(8)
	v_mfma_f32_32x32x16_bf16 v[48:63], v[80:83], v[156:159], v[48:63]
	v_add_f32_e32 v250, v123, v250
	v_add_f32_e32 v250, v124, v250
	v_mfma_f32_32x32x16_bf16 v[32:47], v[84:87], v[156:159], v[32:47]
	v_add_f32_e32 v250, v125, v250
	v_add_f32_e32 v250, v126, v250
	v_mfma_f32_32x32x16_bf16 v[16:31], v[88:91], v[156:159], v[16:31]
	v_add_f32_e32 v250, v127, v250
	v_mfma_f32_32x32x16_bf16 v[0:15], v[92:95], v[156:159], v[0:15]
	v_add_f32_e32 v181, v181, v250
.LBB0_362:
	s_cmp_ge_u32 s66, s16
	s_cbranch_scc1 .LBB0_364
	s_waitcnt lgkmcnt(0)
	v_mfma_f32_32x32x16_bf16 v[96:111], v[200:203], v[128:131], v[232:247]
	v_mfma_f32_32x32x16_bf16 v[112:127], v[204:207], v[128:131], v[232:247]
	v_mfma_f32_32x32x16_bf16 v[96:111], v[208:211], v[132:135], v[96:111]
	v_mfma_f32_32x32x16_bf16 v[112:127], v[212:215], v[132:135], v[112:127]
	v_mfma_f32_32x32x16_bf16 v[96:111], v[216:219], v[136:139], v[96:111]
	v_mfma_f32_32x32x16_bf16 v[112:127], v[220:223], v[136:139], v[112:127]
	v_mfma_f32_32x32x16_bf16 v[96:111], v[224:227], v[140:143], v[96:111]
	v_mfma_f32_32x32x16_bf16 v[112:127], v[228:231], v[140:143], v[112:127]
	s_setprio 0

; #define D_BAR do { asm volatile("" ::: "memory"); __builtin_amdgcn_s_barrier(); asm volatile("" ::: "memory"); } while (0)
; DI void diff_core(unsigned char* smem, const u16* qptr, const u16* kbase, const u16* vtbase, int vld,
;                   int ntb, int ntw, int nvalid, int ks0, const float* lut, int qpos, bool active, bool grpB,
;                   f32x16 (&O)[4], float& l_out) {
;     ...
;     float ps = 0.f;
; #pragma unroll
;     for (int kb = 0; kb < 2; ++kb)
; #pragma unroll
;       for (int i = 0; i < 16; ++i) {
;         const float pe = __builtin_amdgcn_exp2f(S[kb][i]);
;         S[kb][i] = pe;
;         ps += pe;
;       }
;     l += ps;
; #pragma unroll
;     for (int kb = 0; kb < 2; ++kb)
; #pragma unroll
;       for (int s2 = 0; s2 < 2; ++s2) {
;         u32x4 pk;
;         pk.x = pack2(S[kb][8 * s2 + 0], S[kb][8 * s2 + 1]);
;         pk.y = pack2(S[kb][8 * s2 + 2], S[kb][8 * s2 + 3]);
;         pk.z = pack2(S[kb][8 * s2 + 4], S[kb][8 * s2 + 5]);
;         pk.w = pack2(S[kb][8 * s2 + 6], S[kb][8 * s2 + 7]);
;         P[kb * 2 + s2] = pk;
;       }
;     ...
;       if (act_t) softmax(t);
;       asm volatile("s_waitcnt vmcnt(4)" ::: "memory");
;       D_BAR;
;       if (act_t) pv(t & 3);
;       __builtin_amdgcn_sched_barrier(0);
;       if (active && (t + 1) < ntw) qk((t + 1) & 3);
.LBB0_383:
	v_exp_f32_e32 v80, v80
	v_exp_f32_e32 v81, v81
	v_exp_f32_e32 v82, v82
	v_exp_f32_e32 v83, v83
	v_exp_f32_e32 v84, v84
	v_exp_f32_e32 v85, v85
	v_exp_f32_e32 v86, v86
	v_exp_f32_e32 v87, v87
	v_exp_f32_e32 v88, v88
	v_exp_f32_e32 v89, v89
	v_exp_f32_e32 v90, v90
	v_exp_f32_e32 v91, v91
	v_exp_f32_e32 v92, v92
	v_exp_f32_e32 v93, v93
	v_exp_f32_e32 v94, v94
	v_exp_f32_e32 v95, v95
	v_exp_f32_e32 v64, v64
	v_exp_f32_e32 v65, v65
	v_exp_f32_e32 v66, v66
	v_exp_f32_e32 v67, v67
	v_exp_f32_e32 v68, v68
	v_exp_f32_e32 v69, v69
	v_exp_f32_e32 v70, v70
	v_exp_f32_e32 v71, v71
	v_exp_f32_e32 v72, v72
	v_exp_f32_e32 v73, v73
	v_exp_f32_e32 v74, v74
	v_exp_f32_e32 v75, v75
	v_exp_f32_e32 v76, v76
	v_exp_f32_e32 v77, v77
	v_exp_f32_e32 v78, v78
	v_exp_f32_e32 v79, v79
	v_cvt_pk_bf16_f32 v144, v80, v81
	v_cvt_pk_bf16_f32 v145, v82, v83
	v_cvt_pk_bf16_f32 v146, v84, v85
	v_cvt_pk_bf16_f32 v147, v86, v87
	v_add_f32_e32 v250, v81, v80
	v_add_f32_e32 v250, v82, v250
	s_setprio 2
	s_waitcnt lgkmcnt(0)
.LBB0_384:
	s_waitcnt vmcnt(4)
	s_barrier
	s_andn2_b64 vcc, exec, s[0:1]
	s_cbranch_vccnz .LBB0_386
	v_mfma_f32_32x32x16_bf16 v[48:63], v[200:203], v[144:147], v[48:63]
	v_cvt_pk_bf16_f32 v148, v88, v89
	v_add_f32_e32 v250, v83, v250
	v_add_f32_e32 v250, v84, v250
	v_add_u32_e32 v97, s100, v186
	ds_read_b128 v[98:101], v97 offset:16384
	ds_read_b128 v[102:105], v97 offset:20480
	ds_read_b128 v[106:109], v97 offset:24576
	ds_read_b128 v[110:113], v97 offset:28672
	v_mfma_f32_32x32x16_bf16 v[32:47], v[204:207], v[144:147], v[32:47]
	v_cvt_pk_bf16_f32 v149, v90, v91
	v_add_f32_e32 v250, v85, v250
	v_add_f32_e32 v250, v86, v250
	v_add_u32_e32 v126, s100, v184
	ds_read_b128 v[114:117], v126 offset:16384
	ds_read_b128 v[118:121], v126 offset:20480
	ds_read_b128 v[122:125], v126 offset:24576
	ds_read_b128 v[196:199], v126 offset:28672
	v_mfma_f32_32x32x16_bf16 v[16:31], v[208:211], v[144:147], v[16:31]
	v_cvt_pk_bf16_f32 v150, v92, v93
	v_add_f32_e32 v250, v87, v250
	v_add_f32_e32 v250, v88, v250
	v_mfma_f32_32x32x16_bf16 v[0:15], v[212:215], v[144:147], v[0:15]
	v_cvt_pk_bf16_f32 v151, v94, v95
	v_add_f32_e32 v250, v89, v250
	v_add_f32_e32 v250, v90, v250
	v_mfma_f32_32x32x16_bf16 v[48:63], v[216:219], v[148:151], v[48:63]
	v_cvt_pk_bf16_f32 v152, v64, v65
	v_add_f32_e32 v250, v91, v250
	v_add_f32_e32 v250, v92, v250
	v_mfma_f32_32x32x16_bf16 v[32:47], v[220:223], v[148:151], v[32:47]
	v_cvt_pk_bf16_f32 v153, v66, v67
	v_add_f32_e32 v250, v93, v250
	v_add_f32_e32 v250, v94, v250
	v_mfma_f32_32x32x16_bf16 v[16:31], v[224:227], v[148:151], v[16:31]
	v_cvt_pk_bf16_f32 v154, v68, v69
	v_add_f32_e32 v250, v95, v250
	v_add_f32_e32 v250, v64, v250
	v_mfma_f32_32x32x16_bf16 v[0:15], v[228:231], v[148:151], v[0:15]
	v_cvt_pk_bf16_f32 v155, v70, v71
	v_add_f32_e32 v250, v65, v250
	v_add_f32_e32 v250, v66, v250
	v_add_u32_e32 v97, s101, v177
	ds_read_b128 v[200:203], v97
	ds_read_b128 v[204:207], v97 offset:8192
	v_add_u32_e32 v126, s101, v178
	ds_read_b128 v[208:211], v126
	ds_read_b128 v[212:215], v126 offset:8192
	s_waitcnt lgkmcnt(8)
	v_mfma_f32_32x32x16_bf16 v[48:63], v[98:101], v[152:155], v[48:63]
	v_cvt_pk_bf16_f32 v156, v72, v73
	v_add_f32_e32 v250, v67, v250
	v_add_f32_e32 v250, v68, v250
	v_mfma_f32_32x32x16_bf16 v[32:47], v[102:105], v[152:155], v[32:47]
	v_cvt_pk_bf16_f32 v157, v74, v75
	v_add_f32_e32 v250, v69, v250
	v_add_f32_e32 v250, v70, v250
	v_mfma_f32_32x32x16_bf16 v[16:31], v[106:109], v[152:155], v[16:31]
	v_cvt_pk_bf16_f32 v158, v76, v77
	v_add_f32_e32 v250, v71, v250
	v_add_f32_e32 v250, v72, v250
	v_mfma_f32_32x32x16_bf16 v[0:15], v[110:113], v[152:155], v[0:15]
	v_cvt_pk_bf16_f32 v159, v78, v79
	v_add_f32_e32 v250, v73, v250
	v_add_f32_e32 v250, v74, v250
	v_add_u32_e32 v97, s101, v179
	ds_read_b128 v[216:219], v97
	ds_read_b128 v[220:223], v97 offset:8192
	v_add_u32_e32 v126, s101, v180
	ds_read_b128 v[224:227], v126
	ds_read_b128 v[228:231], v126 offset:8192
	s_waitcnt lgkmcnt(8)
	v_mfma_f32_32x32x16_bf16 v[48:63], v[114:117], v[156:159], v[48:63]
	v_add_f32_e32 v250, v75, v250
	v_add_f32_e32 v250, v76, v250
	v_mfma_f32_32x32x16_bf16 v[32:47], v[118:121], v[156:159], v[32:47]
	v_add_f32_e32 v250, v77, v250
	v_add_f32_e32 v250, v78, v250
	v_mfma_f32_32x32x16_bf16 v[16:31], v[122:125], v[156:159], v[16:31]
	v_add_f32_e32 v250, v79, v250
	v_mfma_f32_32x32x16_bf16 v[0:15], v[196:199], v[156:159], v[0:15]
	v_add_f32_e32 v181, v181, v250
.LBB0_386:
	s_add_i32 s0, s62, 0x102
	s_cmp_ge_u32 s0, s16
	s_cbranch_scc1 .LB_dma_only
	s_waitcnt lgkmcnt(0)
	s_mov_b32 m0, s85
	v_mfma_f32_32x32x16_bf16 v[80:95], v[200:203], v[128:131], v[232:247]
	global_load_lds_dwordx4 v162, s[86:87]
	v_mfma_f32_32x32x16_bf16 v[64:79], v[204:207], v[128:131], v[232:247]
	s_mov_b32 m0, s65
	v_mfma_f32_32x32x16_bf16 v[80:95], v[208:211], v[132:135], v[80:95]
	global_load_lds_dwordx4 v170, s[86:87]
	v_mfma_f32_32x32x16_bf16 v[64:79], v[212:215], v[132:135], v[64:79]
	s_mov_b32 m0, s88
	v_mfma_f32_32x32x16_bf16 v[80:95], v[216:219], v[136:139], v[80:95]
	global_load_lds_dwordx4 v166, s[66:67]
	v_mfma_f32_32x32x16_bf16 v[64:79], v[220:223], v[136:139], v[64:79]
	s_mov_b32 m0, s89
	v_mfma_f32_32x32x16_bf16 v[80:95], v[224:227], v[140:143], v[80:95]
	global_load_lds_dwordx4 v168, s[66:67]
	v_mfma_f32_32x32x16_bf16 v[64:79], v[228:231], v[140:143], v[64:79]
	s_setprio 0
	s_branch .LBB0_377
